# post-GU group barrier skips the L2 writeback too when the group shares one XCD (converted weights now written through); pool-mixer pair barrier writeback only if the group spans XCDs
# baseline (speedup 1.0000x reference)
; __device__ __forceinline__ unsigned xb_add(unsigned* p, unsigned v) { return __hip_atomic_fetch_add(p, v, __ATOMIC_RELAXED, __HIP_MEMORY_SCOPE_AGENT); }
; __device__ __forceinline__ void xcd_barrier(const XcdBarrier& b, bool tid0) {
;     asm volatile("s_waitcnt vmcnt(0)" ::: "memory");
;     __syncthreads();
;     if (tid0) {
;         unsigned* bar = b.bar;
;         __builtin_amdgcn_s_waitcnt(0);
;         unsigned nloc = b.st[0], nx = b.st[1];
;         if (nloc == 0u) { xcd_barrier_complete(bar, b.x, b.G, nloc, nx); b.st[0] = nloc; b.st[1] = nx; }
;         const unsigned old = xb_add(&bar[XB_XSUB(b.x)], 1u);
;         const unsigned gen = old / nloc;
;         if (old + 1u == (gen + 1u) * nloc) {
;             __builtin_amdgcn_fence(__ATOMIC_RELEASE, "agent");
;             asm volatile("s_waitcnt vmcnt(0)" ::: "memory");
;             const unsigned og = xb_add(&bar[XB_TOP], 1u);
.LBB0_203:
	s_andn2_saveexec_b64 s[0:1], s[8:9]
	s_cbranch_execz .LBB0_223
	s_mov_b64 s[0:1], exec
	v_mov_b32_e32 v1, 0x23fe4
	ds_read_b32 v1, v1
	s_waitcnt lgkmcnt(0)
	v_cmp_eq_u32_e32 vcc, 1, v1
	s_cbranch_vccnz .Lskipwb_pair
	buffer_wbl2 sc1
.Lskipwb_pair:
	s_waitcnt lgkmcnt(0)
	s_waitcnt vmcnt(0)
	v_mbcnt_lo_u32_b32 v1, s0, 0
	v_mbcnt_hi_u32_b32 v1, s1, v1
	v_cmp_eq_u32_e32 vcc, 0, v1
	s_and_saveexec_b64 s[8:9], vcc
	s_cbranch_execz .LBB0_206
	s_bcnt1_i32_b64 s0, s[0:1]
	v_mov_b32_e32 v2, s0
	v_mov_b32_e32 v3, 0x26123000
	global_atomic_add v2, v3, v2, s[4:5] offset:1024 sc0

; __device__ __forceinline__ unsigned xb_add(unsigned* p, unsigned v) { return __hip_atomic_fetch_add(p, v, __ATOMIC_RELAXED, __HIP_MEMORY_SCOPE_AGENT); }
; __device__ __forceinline__ void xcd_barrier(const XcdBarrier& b, bool tid0) {
;     asm volatile("s_waitcnt vmcnt(0)" ::: "memory");
;     __syncthreads();
;     if (tid0) {
;         unsigned* bar = b.bar;
;         __builtin_amdgcn_s_waitcnt(0);
;         unsigned nloc = b.st[0], nx = b.st[1];
;         if (nloc == 0u) { xcd_barrier_complete(bar, b.x, b.G, nloc, nx); b.st[0] = nloc; b.st[1] = nx; }
;         const unsigned old = xb_add(&bar[XB_XSUB(b.x)], 1u);
;         const unsigned gen = old / nloc;
;         if (old + 1u == (gen + 1u) * nloc) {
;             __builtin_amdgcn_fence(__ATOMIC_RELEASE, "agent");
;             asm volatile("s_waitcnt vmcnt(0)" ::: "memory");
;             const unsigned og = xb_add(&bar[XB_TOP], 1u);
.LBB0_745:
	s_andn2_saveexec_b64 s[0:1], s[12:13]
	s_cbranch_execz .LBB0_765
	s_waitcnt lgkmcnt(0)
	v_cmp_eq_u32_e32 vcc, 1, v0
	s_cbranch_vccnz .Lfastbar_6
	s_mov_b64 s[0:1], exec
	buffer_wbl2 sc1
	s_waitcnt lgkmcnt(0)
	s_waitcnt vmcnt(0)
	v_mbcnt_lo_u32_b32 v1, s0, 0
	v_mbcnt_hi_u32_b32 v1, s1, v1
	v_cmp_eq_u32_e32 vcc, 0, v1
	s_and_saveexec_b64 s[12:13], vcc
	s_cbranch_execz .LBB0_748
	s_bcnt1_i32_b64 s0, s[0:1]
	v_mov_b32_e32 v2, s0
	v_mov_b32_e32 v3, 0x3000
	global_atomic_add v2, v3, v2, s[8:9] offset:1024 sc0
